# attention item prologue: first compressed block K/V loads issued before the wait for the Q/rope/gate loads (vmcnt(2))
# baseline (speedup 1.0000x reference)
.LBB0_217:
	s_or_b64 exec, exec, s[0:1]
	s_abs_i32 s1, s90
	s_mul_hi_u32 s8, s1, s89
	s_mul_i32 s9, s8, s88
	s_ashr_i32 s0, s90, 31
	s_sub_i32 s1, s1, s9
	s_xor_b32 s0, s0, s71
	s_add_i32 s9, s8, 1
	s_sub_i32 s10, s1, s88
	s_cmp_ge_u32 s1, s88
	s_cselect_b32 s8, s9, s8
	s_cselect_b32 s1, s10, s1
	s_add_i32 s9, s8, 1
	s_cmp_ge_u32 s1, s88
	s_cselect_b32 s1, s9, s8
	s_xor_b32 s1, s1, s0
	s_sub_i32 s0, s1, s0
	s_mul_i32 s1, s0, s63
	s_sub_i32 s8, s90, s1
	s_ashr_i32 s1, s8, 5
	s_not_b32 s10, s1
	s_mul_i32 s9, s0, s34
	s_and_b32 s0, s0, 1
	s_add_i32 s10, s34, s10
	s_cmp_eq_u32 s0, 0
	s_cselect_b32 s0, s1, s10
	s_add_i32 s9, s0, s9
	s_ashr_i32 s10, s90, 5
	s_and_b64 s[0:1], s[84:85], exec
	s_cselect_b32 s0, s8, s90
	s_cselect_b32 s67, s9, s10
	s_and_b32 s68, s0, 31
	s_bfe_u32 s1, s0, 0x30002
	s_lshl_b32 s0, s0, 2
	s_lshl_b32 s91, s67, 6
	s_lshl_b32 s94, s1, 12
	s_lshl_b32 s1, s1, 4
	s_and_b32 s8, s0, 12
	s_add_i32 s91, s91, s35
	s_or_b32 s0, s1, s8
	v_or_b32_e32 v192, s91, v195
	v_or_b32_e32 v0, s0, v201
	v_ashrrev_i32_e32 v193, 31, v192
	v_lshlrev_b32_e32 v0, 12, v0
	v_lshl_add_u64 v[2:3], v[192:193], 0, v[0:1]
	v_lshlrev_b64 v[2:3], 7, v[2:3]
	v_lshl_add_u64 v[190:191], v[192:193], 0, s[94:95]
	v_lshl_add_u64 v[2:3], v[172:173], 0, v[2:3]
	global_load_dwordx4 v[110:113], v[2:3], off
	global_load_dwordx4 v[82:85], v[2:3], off offset:32
	global_load_dwordx4 v[114:117], v[2:3], off offset:64
	global_load_dwordx4 v[86:89], v[2:3], off offset:96
	v_lshlrev_b64 v[2:3], 8, v[190:191]
	v_lshl_add_u64 v[2:3], v[174:175], 0, v[2:3]
	global_load_dwordx4 v[126:129], v[2:3], off
	global_load_dwordx4 v[122:125], v[2:3], off offset:16
	global_load_dwordx4 v[118:121], v[2:3], off offset:32
	global_load_dwordx4 v[106:109], v[2:3], off offset:48
	global_load_dwordx4 v[102:105], v[2:3], off offset:128
	global_load_dwordx4 v[98:101], v[2:3], off offset:144
	global_load_dwordx4 v[94:97], v[2:3], off offset:160
	global_load_dwordx4 v[90:93], v[2:3], off offset:176
	v_mov_b64_e32 v[2:3], s[82:83]
	s_movk_i32 s9, 0xc0
	v_mad_u64_u32 v[2:3], s[0:1], v190, s9, v[2:3]
	s_sub_i32 s0, s91, 24
	s_ashr_i32 s10, s0, 4
	s_lshl_b32 s0, s67, 2
	s_addk_i32 s0, 0x42
	v_or_b32_e32 v189, s8, v201
	s_ashr_i32 s8, s0, 6
	s_lshl_b64 s[0:1], -1, s8
	s_or_b32 s61, s91, 7
	s_not_b64 s[0:1], s[0:1]
	s_cmp_lt_i32 s8, 64
	v_mul_u32_u24_e32 v0, 3, v189
	s_cselect_b32 s1, s1, -1
	s_cselect_b32 s0, s0, -1
	s_lshl_b32 s94, s68, 15
	v_mad_i32_i24 v3, v191, s9, v3
	v_lshlrev_b32_e32 v0, 2, v0
	s_add_u32 s8, s38, s94
	v_lshl_add_u64 v[2:3], v[2:3], 0, v[0:1]
	s_addc_u32 s9, s39, 0
	s_ff1_i32_b64 s26, s[0:1]
	global_load_dwordx3 v[154:156], v[2:3], off
	s_cmp_gt_i32 s61, 30
	v_lshl_add_u32 v2, s26, 6, v176
	s_cselect_b32 s19, s10, -1
	s_sub_i32 s10, s91, 31
	v_ashrrev_i32_e32 v3, 31, v2
	s_ashr_i32 s10, s10, 4
	v_lshlrev_b64 v[2:3], 7, v[2:3]
	s_cmp_gt_i32 s91, 30
	v_lshl_add_u64 v[2:3], s[8:9], 0, v[2:3]
	v_mov_b32_e32 v187, v1
	s_cselect_b32 s24, s10, -1
	s_add_u32 s10, s0, -1
	v_lshl_add_u64 v[2:3], v[2:3], 0, v[186:187]
	s_addc_u32 s11, s1, -1
	global_load_dwordx4 v[130:133], v[2:3], off
	v_lshl_add_u64 v[2:3], v[178:179], 0, s[94:95]
	s_lshl_b32 s94, s26, 7
	v_lshl_add_u64 v[4:5], v[2:3], 0, s[94:95]
	v_lshl_add_u64 v[4:5], v[4:5], 0, v[186:187]
	global_load_dwordx4 v[134:137], v[4:5], off
	s_waitcnt vmcnt(2)
	v_subrev_u32_e32 v0, 31, v192
	v_ashrrev_i32_e32 v0, 4, v0
	v_cmp_lt_i32_e32 vcc, 30, v192
	v_add_u32_e32 v0, 1, v0
	v_lshl_add_u64 v[198:199], v[2:3], 0, v[186:187]
	v_mov_b32_e32 v2, v1
	v_mov_b32_e32 v3, v1
	v_mov_b32_e32 v4, v1
	v_mov_b32_e32 v5, v1
	v_mov_b32_e32 v6, v1
	v_mov_b32_e32 v7, v1
	v_mov_b32_e32 v8, v1
	v_mov_b32_e32 v9, v1
	v_mov_b32_e32 v10, v1
	v_mov_b32_e32 v11, v1
	v_mov_b32_e32 v12, v1
	v_mov_b32_e32 v13, v1
	v_mov_b32_e32 v14, v1
	v_mov_b32_e32 v15, v1
	v_mov_b32_e32 v16, v1
	v_mov_b32_e32 v17, v1
	v_mov_b32_e32 v18, v1
	v_mov_b32_e32 v19, v1
	v_mov_b32_e32 v20, v1
	v_mov_b32_e32 v21, v1
	v_mov_b32_e32 v22, v1
	v_mov_b32_e32 v23, v1
	v_mov_b32_e32 v24, v1
	v_mov_b32_e32 v25, v1
	v_mov_b32_e32 v26, v1
	v_mov_b32_e32 v27, v1
	v_mov_b32_e32 v28, v1
	v_mov_b32_e32 v29, v1
	v_mov_b32_e32 v30, v1
	v_mov_b32_e32 v31, v1
	v_mov_b32_e32 v48, v1
	v_mov_b32_e32 v49, v1
	v_cndmask_b32_e32 v194, 0, v0, vcc
	v_mov_b32_e32 v0, v1
	v_mov_b32_e32 v34, v1
	v_mov_b32_e32 v35, v1
	v_mov_b32_e32 v36, v1
	v_mov_b32_e32 v37, v1
	v_mov_b32_e32 v38, v1
	v_mov_b32_e32 v39, v1
	v_mov_b32_e32 v40, v1
	v_mov_b32_e32 v41, v1
	v_mov_b32_e32 v42, v1
	v_mov_b32_e32 v43, v1
	v_mov_b32_e32 v44, v1
	v_mov_b32_e32 v45, v1
	v_mov_b32_e32 v46, v1
	v_mov_b32_e32 v47, v1
	v_mov_b64_e32 v[64:65], v[48:49]
	v_mov_b64_e32 v[32:33], v[30:31]
	s_mov_b32 s18, 0
	s_and_b64 s[20:21], s[10:11], s[0:1]
	v_lshl_add_u64 v[196:197], s[8:9], 0, v[186:187]
	v_add_u32_e32 v157, -1, v194
	v_cmp_lt_i32_e64 s[8:9], 0, v194
	v_cmp_gt_i32_e64 s[10:11], 1, v194
	v_mov_b32_e32 v200, v194
	v_mov_b32_e32 v167, v194
	v_mov_b32_e32 v209, 0xf149f2ca
	v_mov_b32_e32 v187, 0
	v_mov_b64_e32 v[62:63], v[46:47]
	v_mov_b64_e32 v[60:61], v[44:45]
	v_mov_b64_e32 v[58:59], v[42:43]
	v_mov_b64_e32 v[56:57], v[40:41]
	v_mov_b64_e32 v[54:55], v[38:39]
	v_mov_b64_e32 v[52:53], v[36:37]
	v_mov_b64_e32 v[50:51], v[34:35]
	v_mov_b64_e32 v[30:31], v[28:29]
	v_mov_b64_e32 v[28:29], v[26:27]
	v_mov_b64_e32 v[26:27], v[24:25]
	v_mov_b64_e32 v[24:25], v[22:23]
	v_mov_b64_e32 v[22:23], v[20:21]
	v_mov_b64_e32 v[20:21], v[18:19]
	v_mov_b64_e32 v[18:19], v[16:17]
	v_mov_b64_e32 v[16:17], v[14:15]
	v_mov_b64_e32 v[14:15], v[12:13]
	v_mov_b64_e32 v[12:13], v[10:11]
	v_mov_b64_e32 v[10:11], v[8:9]
	v_mov_b64_e32 v[8:9], v[6:7]
	v_mov_b64_e32 v[6:7], v[4:5]
	v_mov_b64_e32 v[4:5], v[2:3]
	v_mov_b64_e32 v[2:3], v[0:1]
	s_waitcnt vmcnt(0) lgkmcnt(0)
	ds_write_b128 v203, v[130:133]
	ds_write_b128 v203, v[134:137] offset:9216
	s_branch .LBB0_221
